# full stack: v42 plus conv-weight hoist, SWA bias lookup batching and 59 redundant lgkmcnt(0) waits removed
# speedup vs baseline: 1.0007x; 1.0007x over previous
; #define LAS __attribute__((address_space(3)))
; __device__ __forceinline__ void swa_unit(const Ctx& C, const Params& p, int l, int unit) {
;     ...
;         for (int kt = my_lo; kt <= my_hi; ++kt) {
;             const LAS unsigned char* Kb = lds + (kt - kt_lo) * STILE; const LAS unsigned char* Vb = Kb + 64 * SROW;
;             const int k0 = kt * 64;
;             f32x4 s[2][4];
; #pragma unroll
;             for (int blk = 0; blk < 4; ++blk) {
;                 bf16x8 kf[2];
; #pragma unroll
;                 for (int kk = 0; kk < 2; ++kk) kf[kk] = *(const LAS bf16x8*)(Kb + (blk * 16 + fr) * SROW + (kk * 32 + fq * 8) * 2);
; #pragma unroll
;                 for (int g = 0; g < 2; ++g) { f32x4 a = (f32x4){0.f, 0.f, 0.f, 0.f};
; #pragma unroll
;                     for (int kk = 0; kk < 2; ++kk) a = __builtin_amdgcn_mfma_f32_16x16x32_bf16(kf[kk], qf[g][kk], a, 0, 0, 0);
;                     s[g][blk] = a; }
;             }
;             bf16x8 pf[2][2];
; #pragma unroll
;             for (int g = 0; g < 2; ++g) {
;                 const int qi = q0w + 16 * g + fr;
; #pragma unroll
;                 for (int blk = 0; blk < 4; ++blk) { const int4 t4 = *(const int4*)(p.pos + tok0 + k0 + blk * 16 + fq * 4); const int pkv[4] = {t4.x, t4.y, t4.z, t4.w};
; #pragma unroll
;                     for (int j = 0; j < 4; ++j) { const int key = k0 + blk * 16 + fq * 4 + j; int dd = pq[g] - pkv[j]; dd = dd < 0 ? 0 : (dd > 128 ? 128 : dd);
;                         const float v = s[g][blk][j] * c2 + bth[dd]; const bool ok = (key <= qi) && (qi - key < 128); s[g][blk][j] = ok ? v : -1e30f; } }
.LBB0_276:
	global_load_dwordx4 v[198:201], v[102:103], off
	global_load_dwordx4 v[202:205], v[102:103], off offset:64
	global_load_dwordx4 v[206:209], v[102:103], off offset:128
	global_load_dwordx4 v[210:213], v[102:103], off offset:192
	ds_read_b128 v[50:53], v126
	s_nop 0
	ds_read_b128 v[54:57], v126 offset:64
	v_mov_b32_e32 v129, v66
	v_mov_b32_e32 v108, v0
	v_cmp_le_i32_e32 vcc, v127, v118
	s_waitcnt vmcnt(7) lgkmcnt(1)
	v_mfma_f32_16x16x32_bf16 v[58:61], v[50:53], v[2:5], 0
	v_add_u32_e32 v150, 2, v127
	v_add_u32_e32 v151, 3, v127
	v_add_u32_e32 v152, 17, v127
	s_waitcnt vmcnt(5)
	v_mfma_f32_16x16x32_bf16 v[50:53], v[50:53], v[10:13], 0
	v_add_u32_e32 v153, 18, v127
	v_add_u32_e32 v154, 19, v127
	v_add_u32_e32 v155, 32, v127
	s_waitcnt lgkmcnt(0)
	v_mfma_f32_16x16x32_bf16 v[78:81], v[54:57], v[6:9], v[58:61]
	v_add_u32_e32 v156, 33, v127
	v_add_u32_e32 v157, 34, v127
	v_add_u32_e32 v158, 35, v127
	s_waitcnt vmcnt(4)
	v_mfma_f32_16x16x32_bf16 v[70:73], v[54:57], v[14:17], v[50:53]
	s_nop 2
	ds_read_b128 v[50:53], v126 offset:2304
	ds_read_b128 v[54:57], v126 offset:2368
	v_add_u32_e32 v159, 48, v127
	v_subrev_u32_e32 v128, 64, v109
	s_waitcnt lgkmcnt(1)
	v_mfma_f32_16x16x32_bf16 v[58:61], v[50:53], v[2:5], 0
	v_cmp_gt_i32_e64 s[62:63], s26, v128
	v_add_u32_e32 v160, 49, v127
	v_add_u32_e32 v161, 50, v127
	v_mfma_f32_16x16x32_bf16 v[50:53], v[50:53], v[10:13], 0
	v_add_u32_e32 v162, 51, v127
	s_add_i32 s9, s9, 1
	s_waitcnt lgkmcnt(0)
	v_mfma_f32_16x16x32_bf16 v[82:85], v[54:57], v[6:9], v[58:61]
	v_mfma_f32_16x16x32_bf16 v[66:69], v[54:57], v[14:17], v[50:53]
	s_nop 2
	ds_read_b128 v[50:53], v126 offset:4608
	ds_read_b128 v[58:61], v126 offset:4672
	s_waitcnt lgkmcnt(1)
	v_mfma_f32_16x16x32_bf16 v[54:57], v[50:53], v[2:5], 0
	v_mfma_f32_16x16x32_bf16 v[50:53], v[50:53], v[10:13], 0
	s_waitcnt lgkmcnt(0)
	v_mfma_f32_16x16x32_bf16 v[54:57], v[58:61], v[6:9], v[54:57]
	v_mfma_f32_16x16x32_bf16 v[62:65], v[58:61], v[14:17], v[50:53]
	ds_read_b128 v[58:61], v126 offset:6912
	ds_read_b128 v[74:77], v126 offset:6976
	v_add_u32_e32 v126, 0x4800, v126
	s_waitcnt lgkmcnt(1)
	v_mfma_f32_16x16x32_bf16 v[50:53], v[58:61], v[2:5], 0
	v_mfma_f32_16x16x32_bf16 v[58:61], v[58:61], v[10:13], 0
	s_waitcnt lgkmcnt(0)
	v_mfma_f32_16x16x32_bf16 v[50:53], v[74:77], v[6:9], v[50:53]
	v_mfma_f32_16x16x32_bf16 v[58:61], v[74:77], v[14:17], v[58:61]
	s_waitcnt vmcnt(3)
	v_mov_b32_e32 v74, v198
	v_mov_b32_e32 v75, v199
	v_mov_b32_e32 v76, v200
	v_mov_b32_e32 v77, v201
	v_sub_u32_e32 v0, v114, v74
	v_med3_i32 v0, v0, 0, v180
	v_lshl_add_u32 v0, v0, 2, s8
	ds_read_b32 v0, v0
	v_sub_u32_e32 v74, v115, v74
	v_med3_i32 v74, v74, 0, v180
	v_lshl_add_u32 v74, v74, 2, s8
	ds_read_b32 v74, v74
	s_waitcnt lgkmcnt(1)
	v_fmac_f32_e32 v0, 0x3e38aa3b, v78
	v_add_u32_e32 v78, -16, v109
	v_cmp_gt_i32_e64 s[0:1], s26, v78
	s_and_b64 vcc, vcc, s[0:1]
	v_cndmask_b32_e32 v104, v181, v0, vcc
	v_sub_u32_e32 v214, v114, v75
	v_med3_i32 v214, v214, 0, v180
	v_lshl_add_u32 v214, v214, 2, s8
	ds_read_b32 v214, v214
	v_sub_u32_e32 v215, v114, v76
	v_med3_i32 v215, v215, 0, v180
	v_lshl_add_u32 v215, v215, 2, s8
	ds_read_b32 v215, v215
	v_sub_u32_e32 v216, v114, v77
	v_med3_i32 v216, v216, 0, v180
	v_lshl_add_u32 v216, v216, 2, s8
	ds_read_b32 v216, v216
	v_subrev_u32_e32 v78, 17, v109
	v_cmp_lt_i32_e64 s[0:1], v127, v118
	v_cmp_gt_i32_e64 s[36:37], s26, v78
	s_and_b64 s[0:1], s[0:1], s[36:37]
	s_waitcnt lgkmcnt(0)
	v_fmac_f32_e32 v214, 0x3e38aa3b, v79
	v_cndmask_b32_e64 v105, v181, v214, s[0:1]
	v_subrev_u32_e32 v78, 18, v109
	v_cmp_le_i32_e64 s[0:1], v150, v118
	v_cmp_gt_i32_e64 s[38:39], s26, v78
	s_and_b64 s[0:1], s[0:1], s[38:39]
	v_fmac_f32_e32 v215, 0x3e38aa3b, v80
	v_cndmask_b32_e64 v106, v181, v215, s[0:1]
	v_subrev_u32_e32 v78, 19, v109
	v_cmp_gt_i32_e64 s[40:41], s26, v78
	v_cmp_le_i32_e64 s[0:1], v151, v118
	s_and_b64 s[0:1], s[0:1], s[40:41]
	v_fmac_f32_e32 v216, 0x3e38aa3b, v81
	s_waitcnt vmcnt(2)
	v_mov_b32_e32 v78, v202
	v_mov_b32_e32 v79, v203
	v_mov_b32_e32 v80, v204
	v_mov_b32_e32 v81, v205
	v_cndmask_b32_e64 v107, v181, v216, s[0:1]
	v_add_u32_e32 v0, 16, v127
	v_cmp_le_i32_e64 s[0:1], v0, v118
	v_subrev_u32_e32 v0, 32, v109
	v_cmp_gt_i32_e64 s[42:43], s26, v0
	s_and_b64 s[0:1], s[0:1], s[42:43]
	v_fmac_f32_e32 v74, 0x3e38aa3b, v70
	v_max_f32_e32 v130, v106, v107
	v_sub_u32_e32 v86, v114, v78
	v_med3_i32 v86, v86, 0, v180
	v_lshl_add_u32 v86, v86, 2, s8
	v_sub_u32_e32 v0, v114, v79
	ds_read_b32 v86, v86
	v_med3_i32 v0, v0, 0, v180
	v_lshl_add_u32 v0, v0, 2, s8
	ds_read_b32 v0, v0
	s_waitcnt lgkmcnt(1)
	v_fmac_f32_e32 v86, 0x3e38aa3b, v82
	v_subrev_u32_e32 v82, 33, v109
	v_cndmask_b32_e64 v110, v181, v86, s[0:1]
	v_cmp_le_i32_e64 s[0:1], v152, v118
	v_cmp_gt_i32_e64 s[44:45], s26, v82
	s_waitcnt lgkmcnt(0)
	v_fmac_f32_e32 v0, 0x3e38aa3b, v83
	s_and_b64 s[0:1], s[0:1], s[44:45]
	v_cndmask_b32_e64 v111, v181, v0, s[0:1]
	v_sub_u32_e32 v217, v114, v80
	v_med3_i32 v217, v217, 0, v180
	v_lshl_add_u32 v217, v217, 2, s8
	ds_read_b32 v217, v217
	v_sub_u32_e32 v218, v114, v81
	v_med3_i32 v218, v218, 0, v180
	v_lshl_add_u32 v218, v218, 2, s8
	ds_read_b32 v218, v218
	v_subrev_u32_e32 v82, 34, v109
	v_cmp_le_i32_e64 s[0:1], v153, v118
	v_cmp_gt_i32_e64 s[46:47], s26, v82
	s_and_b64 s[0:1], s[0:1], s[46:47]
	s_waitcnt lgkmcnt(0)
	v_fmac_f32_e32 v217, 0x3e38aa3b, v84
	v_cndmask_b32_e64 v112, v181, v217, s[0:1]
	v_subrev_u32_e32 v82, 35, v109
	v_cmp_gt_i32_e64 s[48:49], s26, v82
	s_waitcnt vmcnt(0)
; __device__ __forceinline__ void swa_unit(const Ctx& C, const Params& p, int l, int unit) {
;     ...
;                 for (int blk = 0; blk < 4; ++blk) { const int4 t4 = *(const int4*)(p.pos + tok0 + k0 + blk * 16 + fq * 4); const int pkv[4] = {t4.x, t4.y, t4.z, t4.w};
; #pragma unroll
;                     for (int j = 0; j < 4; ++j) { const int key = k0 + blk * 16 + fq * 4 + j; int dd = pq[g] - pkv[j]; dd = dd < 0 ? 0 : (dd > 128 ? 128 : dd);
;                         const float v = s[g][blk][j] * c2 + bth[dd]; const bool ok = (key <= qi) && (qi - key < 128); s[g][blk][j] = ok ? v : -1e30f; } }
;                 float mx = fmaxf(fmaxf(s[g][0][0], s[g][0][1]), fmaxf(s[g][0][2], s[g][0][3]));
; #pragma unroll
;                 for (int blk = 1; blk < 4; ++blk) mx = fmaxf(mx, fmaxf(fmaxf(s[g][blk][0], s[g][blk][1]), fmaxf(s[g][blk][2], s[g][blk][3])));
;                 mx = rowmax4(mx);
	v_mov_b32_e32 v86, v210
	v_mov_b32_e32 v87, v211
	v_mov_b32_e32 v88, v212
	v_mov_b32_e32 v89, v213
	v_cmp_le_i32_e64 s[0:1], v154, v118
	v_fmac_f32_e32 v218, 0x3e38aa3b, v85
	v_mov_b32_e32 v82, v206
	v_mov_b32_e32 v83, v207
	v_mov_b32_e32 v84, v208
	v_mov_b32_e32 v85, v209
	s_and_b64 s[0:1], s[0:1], s[48:49]
	v_cndmask_b32_e64 v113, v181, v218, s[0:1]
	v_cmp_le_i32_e64 s[0:1], v155, v118
	v_max_f32_e32 v131, v112, v113
	v_max3_f32 v131, v110, v111, v131
	v_sub_u32_e32 v219, v114, v82
	v_med3_i32 v219, v219, 0, v180
	v_lshl_add_u32 v219, v219, 2, s8
	ds_read_b32 v219, v219
	v_sub_u32_e32 v220, v114, v83
	v_med3_i32 v220, v220, 0, v180
	v_lshl_add_u32 v220, v220, 2, s8
	ds_read_b32 v220, v220
	v_sub_u32_e32 v221, v114, v84
	v_med3_i32 v221, v221, 0, v180
	v_lshl_add_u32 v221, v221, 2, s8
	ds_read_b32 v221, v221
	v_sub_u32_e32 v214, v114, v85
	v_med3_i32 v214, v214, 0, v180
	v_lshl_add_u32 v214, v214, 2, s8
	ds_read_b32 v214, v214
	s_waitcnt lgkmcnt(0)
	v_fmac_f32_e32 v219, 0x3e38aa3b, v54
	v_subrev_u32_e32 v54, 48, v109
	v_cmp_gt_i32_e64 s[50:51], s26, v54
	s_and_b64 s[0:1], s[0:1], s[50:51]
	v_cndmask_b32_e64 v54, v181, v219, s[0:1]
	v_cmp_le_i32_e64 s[0:1], v156, v118
	v_fmac_f32_e32 v220, 0x3e38aa3b, v55
	v_subrev_u32_e32 v55, 49, v109
	v_cmp_gt_i32_e64 s[52:53], s26, v55
	s_and_b64 s[0:1], s[0:1], s[52:53]
	v_cndmask_b32_e64 v55, v181, v220, s[0:1]
	v_cmp_le_i32_e64 s[0:1], v157, v118
	v_fmac_f32_e32 v221, 0x3e38aa3b, v56
	v_subrev_u32_e32 v56, 50, v109
	v_cmp_gt_i32_e64 s[54:55], s26, v56
	s_and_b64 s[0:1], s[0:1], s[54:55]
	v_cndmask_b32_e64 v56, v181, v221, s[0:1]
	v_cmp_le_i32_e64 s[0:1], v158, v118
	v_fmac_f32_e32 v214, 0x3e38aa3b, v57
	v_subrev_u32_e32 v57, 51, v109
	v_cmp_gt_i32_e64 s[56:57], s26, v57
	s_and_b64 s[0:1], s[0:1], s[56:57]
	v_cndmask_b32_e64 v57, v181, v214, s[0:1]
	v_sub_u32_e32 v215, v114, v86
	v_med3_i32 v215, v215, 0, v180
	v_lshl_add_u32 v215, v215, 2, s8
	ds_read_b32 v215, v215
	v_sub_u32_e32 v216, v114, v87
	v_med3_i32 v216, v216, 0, v180
	v_lshl_add_u32 v216, v216, 2, s8
	ds_read_b32 v216, v216
	v_sub_u32_e32 v217, v114, v88
	v_med3_i32 v217, v217, 0, v180
	v_lshl_add_u32 v217, v217, 2, s8
	ds_read_b32 v217, v217
	v_sub_u32_e32 v218, v114, v89
	v_med3_i32 v218, v218, 0, v180
	v_lshl_add_u32 v218, v218, 2, s8
	ds_read_b32 v218, v218
	v_cmp_le_i32_e64 s[0:1], v159, v118
	s_and_b64 s[0:1], s[0:1], s[62:63]
	s_waitcnt lgkmcnt(0)
	v_fmac_f32_e32 v215, 0x3e38aa3b, v50
	v_cndmask_b32_e64 v50, v181, v215, s[0:1]
	v_cmp_le_i32_e64 s[0:1], v160, v118
	v_fmac_f32_e32 v216, 0x3e38aa3b, v51
	v_add_u32_e32 v51, 0xffffffbf, v109
	v_cmp_gt_i32_e64 s[62:63], s26, v51
	s_and_b64 s[0:1], s[0:1], s[62:63]
	v_cndmask_b32_e64 v51, v181, v216, s[0:1]
	v_cmp_le_i32_e64 s[0:1], v161, v118
	v_fmac_f32_e32 v217, 0x3e38aa3b, v52
	v_add_u32_e32 v52, 0xffffffbe, v109
	v_cmp_gt_i32_e64 s[62:63], s26, v52
	s_and_b64 s[0:1], s[0:1], s[62:63]
	v_cndmask_b32_e64 v52, v181, v217, s[0:1]
	v_cmp_le_i32_e64 s[0:1], v162, v118
	v_fmac_f32_e32 v218, 0x3e38aa3b, v53
	v_add_u32_e32 v53, 0xffffffbd, v109
	v_cmp_gt_i32_e64 s[62:63], s26, v53
	s_and_b64 s[0:1], s[0:1], s[62:63]
	v_cndmask_b32_e64 v53, v181, v218, s[0:1]
	v_cmp_le_i32_e64 s[0:1], v127, v119
	v_cmp_gt_i32_e64 s[62:63], s26, v109
	s_and_b64 s[0:1], s[0:1], s[62:63]
	v_cndmask_b32_e64 v70, v181, v74, s[0:1]
	v_sub_u32_e32 v219, v115, v75
	v_med3_i32 v219, v219, 0, v180
	v_lshl_add_u32 v219, v219, 2, s8
	ds_read_b32 v219, v219
	v_sub_u32_e32 v220, v115, v76
	v_med3_i32 v220, v220, 0, v180
	v_lshl_add_u32 v220, v220, 2, s8
	ds_read_b32 v220, v220
	v_sub_u32_e32 v221, v115, v77
	v_med3_i32 v221, v221, 0, v180
	v_lshl_add_u32 v221, v221, 2, s8
	ds_read_b32 v221, v221
	v_cmp_lt_i32_e64 s[0:1], v127, v119
	v_max_f32_e32 v0, v104, v105
	v_max3_f32 v0, v0, v130, v131
	v_max_f32_e32 v130, v56, v57
	s_waitcnt lgkmcnt(0)
	v_fmac_f32_e32 v219, 0x3e38aa3b, v71
	v_add_u32_e32 v71, -1, v109
	v_cmp_gt_i32_e64 s[62:63], s26, v71
	s_and_b64 s[0:1], s[0:1], s[62:63]
	v_cndmask_b32_e64 v71, v181, v219, s[0:1]
	v_cmp_le_i32_e64 s[0:1], v150, v119
	v_max_f32_e32 v131, v52, v53
	v_max3_f32 v130, v54, v55, v130
	v_max3_f32 v131, v50, v51, v131
	v_fmac_f32_e32 v220, 0x3e38aa3b, v72
	v_add_u32_e32 v72, -2, v109
	v_cmp_gt_i32_e64 s[62:63], s26, v72
	s_and_b64 s[0:1], s[0:1], s[62:63]
	v_cndmask_b32_e64 v72, v181, v220, s[0:1]
	v_cmp_le_i32_e64 s[0:1], v151, v119
	v_max3_f32 v0, v0, v130, v131
	v_mov_b32_e32 v130, v0
	s_nop 1
	v_permlane16_swap_b32_e32 v0, v130
	v_fmac_f32_e32 v221, 0x3e38aa3b, v73
	v_add_u32_e32 v73, -3, v109
	v_cmp_gt_i32_e64 s[62:63], s26, v73
	s_and_b64 s[0:1], s[0:1], s[62:63]
	v_cndmask_b32_e64 v73, v181, v221, s[0:1]
	v_sub_u32_e32 v74, v115, v78
	v_med3_i32 v74, v74, 0, v180
	v_lshl_add_u32 v74, v74, 2, s8
	ds_read_b32 v74, v74
	v_max_f32_e32 v130, v130, v130
	v_max_f32_e32 v0, v0, v0
	v_max_f32_e32 v0, v0, v130
	v_mov_b32_e32 v130, v0
	s_waitcnt lgkmcnt(0)
	v_fmac_f32_e32 v74, 0x3e38aa3b, v66
	v_sub_u32_e32 v66, v115, v79
	v_med3_i32 v66, v66, 0, v180
	v_lshl_add_u32 v66, v66, 2, s8
	ds_read_b32 v66, v66
	v_cndmask_b32_e32 v74, v181, v74, vcc
	v_cmp_le_i32_e32 vcc, v152, v119
	s_and_b64 vcc, vcc, s[36:37]
	v_permlane32_swap_b32_e32 v0, v130
	s_waitcnt lgkmcnt(0)
	v_fmac_f32_e32 v66, 0x3e38aa3b, v67
	v_cndmask_b32_e32 v75, v181, v66, vcc
	v_sub_u32_e32 v66, v115, v80
	v_med3_i32 v66, v66, 0, v180
	v_lshl_add_u32 v66, v66, 2, s8
	ds_read_b32 v66, v66
	v_cmp_le_i32_e32 vcc, v153, v119
	s_and_b64 vcc, vcc, s[38:39]
	v_max_f32_e32 v67, v72, v73
	v_max3_f32 v0, v108, v0, v130
	s_waitcnt lgkmcnt(0)
; __device__ __forceinline__ void swa_unit(const Ctx& C, const Params& p, int l, int unit) {
;     ...
;                 for (int blk = 0; blk < 4; ++blk) { const int4 t4 = *(const int4*)(p.pos + tok0 + k0 + blk * 16 + fq * 4); const int pkv[4] = {t4.x, t4.y, t4.z, t4.w};
; #pragma unroll
;                     for (int j = 0; j < 4; ++j) { const int key = k0 + blk * 16 + fq * 4 + j; int dd = pq[g] - pkv[j]; dd = dd < 0 ? 0 : (dd > 128 ? 128 : dd);
;                         const float v = s[g][blk][j] * c2 + bth[dd]; const bool ok = (key <= qi) && (qi - key < 128); s[g][blk][j] = ok ? v : -1e30f; } }
;                 float mx = fmaxf(fmaxf(s[g][0][0], s[g][0][1]), fmaxf(s[g][0][2], s[g][0][3]));
; #pragma unroll
;                 for (int blk = 1; blk < 4; ++blk) mx = fmaxf(mx, fmaxf(fmaxf(s[g][blk][0], s[g][blk][1]), fmaxf(s[g][blk][2], s[g][blk][3])));
;                 mx = rowmax4(mx);
;                 const float mn = fmaxf(m[g], mx), alpha = __builtin_amdgcn_exp2f(m[g] - mn); m[g] = mn;
;                 f32x2 ps2 = (f32x2){0.f, 0.f}; const f32x2 mnv = (f32x2){mn, mn};
; #pragma unroll
;                 for (int blk = 0; blk < 4; ++blk)
; #pragma unroll
;                     for (int jp = 0; jp < 2; ++jp) { f32x2 x = (f32x2){s[g][blk][2 * jp], s[g][blk][2 * jp + 1]}; x = x - mnv;
;                         f32x2 pv; pv.x = __builtin_amdgcn_exp2f(x.x); pv.y = __builtin_amdgcn_exp2f(x.y); ps2 = ps2 + pv; s[g][blk][2 * jp] = pv.x; s[g][blk][2 * jp + 1] = pv.y; }
	v_fmac_f32_e32 v66, 0x3e38aa3b, v68
	v_cndmask_b32_e32 v68, v181, v66, vcc
	v_sub_u32_e32 v66, v115, v81
	v_med3_i32 v66, v66, 0, v180
	v_lshl_add_u32 v66, v66, 2, s8
	ds_read_b32 v66, v66
	v_cmp_le_i32_e32 vcc, v154, v119
	s_and_b64 vcc, vcc, s[40:41]
	v_pk_add_f32 v[104:105], v[104:105], v[0:1] op_sel_hi:[1,0] neg_lo:[0,1] neg_hi:[0,1]
	v_pk_add_f32 v[106:107], v[106:107], v[0:1] op_sel_hi:[1,0] neg_lo:[0,1] neg_hi:[0,1]
	s_waitcnt lgkmcnt(0)
	v_fmac_f32_e32 v66, 0x3e38aa3b, v69
	v_cndmask_b32_e32 v69, v181, v66, vcc
	v_sub_u32_e32 v66, v115, v82
	v_med3_i32 v66, v66, 0, v180
	v_lshl_add_u32 v66, v66, 2, s8
	ds_read_b32 v66, v66
	v_cmp_le_i32_e32 vcc, v155, v119
	s_and_b64 vcc, vcc, s[42:43]
	v_max_f32_e32 v76, v68, v69
	v_max3_f32 v76, v74, v75, v76
	s_waitcnt lgkmcnt(0)
	v_fmac_f32_e32 v66, 0x3e38aa3b, v62
	v_cndmask_b32_e32 v62, v181, v66, vcc
	v_sub_u32_e32 v66, v115, v83
	v_med3_i32 v66, v66, 0, v180
	v_lshl_add_u32 v66, v66, 2, s8
	ds_read_b32 v66, v66
	v_cmp_le_i32_e32 vcc, v156, v119
	s_and_b64 vcc, vcc, s[44:45]
	v_exp_f32_e32 v130, v104
	v_exp_f32_e32 v131, v105
	s_waitcnt lgkmcnt(0)
	v_fmac_f32_e32 v66, 0x3e38aa3b, v63
	v_cndmask_b32_e32 v63, v181, v66, vcc
	v_sub_u32_e32 v66, v115, v84
	v_med3_i32 v66, v66, 0, v180
	v_lshl_add_u32 v66, v66, 2, s8
	ds_read_b32 v66, v66
	v_cmp_le_i32_e32 vcc, v157, v119
	s_and_b64 vcc, vcc, s[46:47]
	v_exp_f32_e32 v106, v106
	v_exp_f32_e32 v107, v107
	s_waitcnt lgkmcnt(0)
	v_fmac_f32_e32 v66, 0x3e38aa3b, v64
	v_cndmask_b32_e32 v64, v181, v66, vcc
	v_sub_u32_e32 v66, v115, v85
	v_med3_i32 v66, v66, 0, v180
	v_lshl_add_u32 v66, v66, 2, s8
	ds_read_b32 v66, v66
	v_cmp_le_i32_e32 vcc, v158, v119
	s_and_b64 vcc, vcc, s[48:49]
	v_pk_add_f32 v[110:111], v[110:111], v[0:1] op_sel_hi:[1,0] neg_lo:[0,1] neg_hi:[0,1]
	v_pk_add_f32 v[112:113], v[112:113], v[0:1] op_sel_hi:[1,0] neg_lo:[0,1] neg_hi:[0,1]
	s_waitcnt lgkmcnt(0)
	v_fmac_f32_e32 v66, 0x3e38aa3b, v65
	v_cndmask_b32_e32 v65, v181, v66, vcc
	v_sub_u32_e32 v66, v115, v86
	v_med3_i32 v66, v66, 0, v180
	v_lshl_add_u32 v66, v66, 2, s8
	ds_read_b32 v66, v66
	v_cmp_le_i32_e32 vcc, v159, v119
	s_and_b64 vcc, vcc, s[50:51]
	v_exp_f32_e32 v110, v110
	v_exp_f32_e32 v111, v111
	s_waitcnt lgkmcnt(0)
	v_fmac_f32_e32 v66, 0x3e38aa3b, v58
	v_cndmask_b32_e32 v58, v181, v66, vcc
	v_sub_u32_e32 v66, v115, v87
	v_med3_i32 v66, v66, 0, v180
	v_lshl_add_u32 v66, v66, 2, s8
	ds_read_b32 v66, v66
	v_cmp_le_i32_e32 vcc, v160, v119
	s_and_b64 vcc, vcc, s[52:53]
	v_exp_f32_e32 v112, v112
	v_exp_f32_e32 v113, v113
	s_waitcnt lgkmcnt(0)
	v_fmac_f32_e32 v66, 0x3e38aa3b, v59
	v_cndmask_b32_e32 v59, v181, v66, vcc
	v_sub_u32_e32 v66, v115, v88
	v_med3_i32 v66, v66, 0, v180
	v_lshl_add_u32 v66, v66, 2, s8
	ds_read_b32 v66, v66
	v_cmp_le_i32_e32 vcc, v161, v119
	s_and_b64 vcc, vcc, s[54:55]
	v_pk_add_f32 v[54:55], v[54:55], v[0:1] op_sel_hi:[1,0] neg_lo:[0,1] neg_hi:[0,1]
	v_pk_add_f32 v[104:105], v[130:131], 0 op_sel_hi:[1,0]
	s_waitcnt lgkmcnt(0)
	v_fmac_f32_e32 v66, 0x3e38aa3b, v60
	v_cndmask_b32_e32 v60, v181, v66, vcc
	v_sub_u32_e32 v66, v115, v89
	v_med3_i32 v66, v66, 0, v180
	v_lshl_add_u32 v66, v66, 2, s8
	ds_read_b32 v66, v66
	v_cmp_le_i32_e32 vcc, v162, v119
	s_and_b64 vcc, vcc, s[56:57]
	v_exp_f32_e32 v132, v54
	v_exp_f32_e32 v133, v55
	s_waitcnt lgkmcnt(0)
; #define LAS __attribute__((address_space(3)))
; __device__ __forceinline__ unsigned pkhw(float lo, float hi) { f32x2q v = {lo, hi}; bf16x2q b = __builtin_convertvector(v, bf16x2q); return __builtin_bit_cast(unsigned, b); }
; __device__ __forceinline__ void swa_unit(const Ctx& C, const Params& p, int l, int unit) {
;     ...
;                 float mx = fmaxf(fmaxf(s[g][0][0], s[g][0][1]), fmaxf(s[g][0][2], s[g][0][3]));
; #pragma unroll
;                 for (int blk = 1; blk < 4; ++blk) mx = fmaxf(mx, fmaxf(fmaxf(s[g][blk][0], s[g][blk][1]), fmaxf(s[g][blk][2], s[g][blk][3])));
;                 mx = rowmax4(mx);
;                 const float mn = fmaxf(m[g], mx), alpha = __builtin_amdgcn_exp2f(m[g] - mn); m[g] = mn;
;                 f32x2 ps2 = (f32x2){0.f, 0.f}; const f32x2 mnv = (f32x2){mn, mn};
; #pragma unroll
;                 for (int blk = 0; blk < 4; ++blk)
; #pragma unroll
;                     for (int jp = 0; jp < 2; ++jp) { f32x2 x = (f32x2){s[g][blk][2 * jp], s[g][blk][2 * jp + 1]}; x = x - mnv;
;                         f32x2 pv; pv.x = __builtin_amdgcn_exp2f(x.x); pv.y = __builtin_amdgcn_exp2f(x.y); ps2 = ps2 + pv; s[g][blk][2 * jp] = pv.x; s[g][blk][2 * jp + 1] = pv.y; }
;                 const float ps = ps2.x + ps2.y;
;                 lsum[g] = lsum[g] * alpha + ps;
; #pragma unroll
;                 for (int d = 0; d < 4; ++d) o[g][d] = o[g][d] * alpha;
; #pragma unroll
;                 for (int hf = 0; hf < 2; ++hf) { v4u pw; pw.x = pkhw(s[g][2 * hf][0], s[g][2 * hf][1]); pw.y = pkhw(s[g][2 * hf][2], s[g][2 * hf][3]); pw.z = pkhw(s[g][2 * hf + 1][0], s[g][2 * hf + 1][1]); pw.w = pkhw(s[g][2 * hf + 1][2], s[g][2 * hf + 1][3]);
;                     pf[g][hf] = __builtin_bit_cast(bf16x8, pw); }
;             }
; #pragma unroll
;             for (int hf = 0; hf < 2; ++hf)
; #pragma unroll
;                 for (int d = 0; d < 4; ++d) {
;                     const LAS unsigned char* vp = Vb + (d * 16 + fr) * SROW + (hf * 32 + fq * 4) * 2;
;                     const v2u lo = *(const LAS v2u*)vp, hi = *(const LAS v2u*)(vp + 32);
;                     const v4u vw = (v4u){lo.x, lo.y, hi.x, hi.y}; const bf16x8 vf = __builtin_bit_cast(bf16x8, vw);
; #pragma unroll
;                     for (int g = 0; g < 2; ++g) o[g][d] = __builtin_amdgcn_mfma_f32_16x16x32_bf16(vf, pf[g][hf], o[g][d], 0, 0, 0);
;                 }
	v_fmac_f32_e32 v66, 0x3e38aa3b, v61
	v_cndmask_b32_e32 v61, v181, v66, vcc
	v_max_f32_e32 v66, v70, v71
	v_max3_f32 v66, v66, v67, v76
	v_max_f32_e32 v67, v64, v65
	v_max_f32_e32 v76, v60, v61
	v_max3_f32 v67, v62, v63, v67
	v_max3_f32 v76, v58, v59, v76
	v_max3_f32 v66, v66, v67, v76
	v_mov_b32_e32 v67, v66
	s_nop 1
	v_permlane16_swap_b32_e32 v66, v67
	v_max_f32_e32 v67, v67, v67
	v_max_f32_e32 v66, v66, v66
	v_max_f32_e32 v66, v66, v67
	v_mov_b32_e32 v67, v66
	s_nop 1
	v_permlane32_swap_b32_e32 v66, v67
	v_max3_f32 v66, v129, v66, v67
	v_sub_f32_e32 v67, v129, v66
	v_pk_add_f32 v[70:71], v[70:71], v[66:67] op_sel_hi:[1,0] neg_lo:[0,1] neg_hi:[0,1]
	v_pk_add_f32 v[72:73], v[72:73], v[66:67] op_sel_hi:[1,0] neg_lo:[0,1] neg_hi:[0,1]
	v_exp_f32_e32 v70, v70
	v_exp_f32_e32 v71, v71
	v_exp_f32_e32 v72, v72
	v_exp_f32_e32 v73, v73
	v_pk_add_f32 v[74:75], v[74:75], v[66:67] op_sel_hi:[1,0] neg_lo:[0,1] neg_hi:[0,1]
	v_pk_add_f32 v[68:69], v[68:69], v[66:67] op_sel_hi:[1,0] neg_lo:[0,1] neg_hi:[0,1]
	v_exp_f32_e32 v74, v74
	v_exp_f32_e32 v75, v75
	v_exp_f32_e32 v68, v68
	v_exp_f32_e32 v69, v69
	v_pk_add_f32 v[62:63], v[62:63], v[66:67] op_sel_hi:[1,0] neg_lo:[0,1] neg_hi:[0,1]
	v_pk_add_f32 v[76:77], v[70:71], 0 op_sel_hi:[1,0]
	v_exp_f32_e32 v78, v62
	v_exp_f32_e32 v79, v63
	v_pk_add_f32 v[76:77], v[72:73], v[76:77]
	v_pk_add_f32 v[56:57], v[56:57], v[0:1] op_sel_hi:[1,0] neg_lo:[0,1] neg_hi:[0,1]
	v_pk_add_f32 v[76:77], v[74:75], v[76:77]
	v_pk_add_f32 v[64:65], v[64:65], v[66:67] op_sel_hi:[1,0] neg_lo:[0,1] neg_hi:[0,1]
	v_pk_add_f32 v[76:77], v[68:69], v[76:77]
	v_pk_add_f32 v[104:105], v[106:107], v[104:105]
	v_exp_f32_e32 v164, v56
	v_exp_f32_e32 v165, v57
	v_pk_add_f32 v[50:51], v[50:51], v[0:1] op_sel_hi:[1,0] neg_lo:[0,1] neg_hi:[0,1]
	v_pk_add_f32 v[62:63], v[78:79], v[76:77]
	v_exp_f32_e32 v76, v64
	v_exp_f32_e32 v77, v65
	v_pk_add_f32 v[58:59], v[58:59], v[66:67] op_sel_hi:[1,0] neg_lo:[0,1] neg_hi:[0,1]
	v_pk_add_f32 v[104:105], v[110:111], v[104:105]
	v_exp_f32_e32 v166, v50
	v_exp_f32_e32 v167, v51
	v_pk_add_f32 v[52:53], v[52:53], v[0:1] op_sel_hi:[1,0] neg_lo:[0,1] neg_hi:[0,1]
	v_exp_f32_e32 v80, v58
	v_exp_f32_e32 v81, v59
	v_pk_add_f32 v[60:61], v[60:61], v[66:67] op_sel_hi:[1,0] neg_lo:[0,1] neg_hi:[0,1]
	v_sub_f32_e32 v108, v108, v0
	v_pk_add_f32 v[104:105], v[112:113], v[104:105]
	v_exp_f32_e32 v168, v52
	v_exp_f32_e32 v169, v53
	v_exp_f32_e32 v82, v60
	v_exp_f32_e32 v83, v61
	v_exp_f32_e32 v108, v108
	v_pk_add_f32 v[54:55], v[132:133], v[104:105]
	v_exp_f32_e32 v109, v67
	v_pk_add_f32 v[54:55], v[164:165], v[54:55]
	v_pk_add_f32 v[62:63], v[76:77], v[62:63]
	v_pk_add_f32 v[50:51], v[166:167], v[54:55]
	v_pk_add_f32 v[58:59], v[80:81], v[62:63]
	v_pk_add_f32 v[104:105], v[168:169], v[50:51]
	v_pk_add_f32 v[62:63], v[82:83], v[58:59]
	v_pk_mul_f32 v[58:59], v[46:47], v[108:109] op_sel_hi:[1,0]
	v_mov_b32_e32 v46, v104
	v_mov_b32_e32 v47, v62
	v_mov_b32_e32 v62, v105
	v_pk_add_f32 v[46:47], v[46:47], v[62:63]
	v_mov_b32_e32 v84, v109
	v_pk_mul_f32 v[60:61], v[48:49], v[108:109] op_sel_hi:[1,0]
	v_pk_fma_f32 v[100:101], v[100:101], v[108:109], v[46:47]
	v_pk_mul_f32 v[48:49], v[28:29], v[84:85] op_sel_hi:[1,0]
	v_pk_mul_f32 v[46:47], v[26:27], v[84:85] op_sel_hi:[1,0]
	v_cvt_pk_bf16_f32 v26, v70, v71
	v_cvt_pk_bf16_f32 v29, v68, v69
	ds_read2_b64 v[68:71], v125 offset1:4
	v_cvt_pk_bf16_f32 v54, v130, v131
	v_cvt_pk_bf16_f32 v55, v106, v107
	v_cvt_pk_bf16_f32 v56, v110, v111
	v_cvt_pk_bf16_f32 v57, v112, v113
	v_pk_mul_f32 v[64:65], v[32:33], v[84:85] op_sel_hi:[1,0]
	v_pk_mul_f32 v[62:63], v[30:31], v[84:85] op_sel_hi:[1,0]
	v_cvt_pk_bf16_f32 v27, v72, v73
	v_cvt_pk_bf16_f32 v28, v74, v75
	v_add_u32_e32 v67, 0x800, v125
	s_waitcnt lgkmcnt(0)
	v_mfma_f32_16x16x32_bf16 v[58:61], v[68:71], v[54:57], v[58:61]
	v_mul_f32_e64 v44, v44, v108
	v_mul_f32_e64 v45, v45, v108
	v_pk_mul_f32 v[42:43], v[42:43], v[108:109] op_sel_hi:[1,0]
	v_pk_mul_f32 v[30:31], v[22:23], v[84:85] op_sel_hi:[1,0]
	v_mfma_f32_16x16x32_bf16 v[62:65], v[68:71], v[26:29], v[62:65]
	ds_read2_b64 v[68:71], v67 offset0:32 offset1:36
	v_pk_mul_f32 v[22:23], v[18:19], v[84:85] op_sel_hi:[1,0]
	v_cvt_pk_bf16_f32 v19, v76, v77
	v_add_u32_e32 v76, 0x1000, v125
	s_waitcnt lgkmcnt(0)
	v_mfma_f32_16x16x32_bf16 v[42:45], v[68:71], v[54:57], v[42:45]
	v_mul_f32_e64 v32, v24, v84
	v_mul_f32_e64 v33, v25, v84
	v_add_u32_e32 v77, 0x1800, v125
	v_pk_mul_f32 v[40:41], v[40:41], v[108:109] op_sel_hi:[1,0]
	v_mfma_f32_16x16x32_bf16 v[68:71], v[68:71], v[26:29], v[46:49]
	v_mul_f32_e64 v38, v38, v108
	v_mul_f32_e64 v39, v39, v108
	v_pk_mul_f32 v[36:37], v[36:37], v[108:109] op_sel_hi:[1,0]
	v_pk_mul_f32 v[34:35], v[34:35], v[108:109] op_sel_hi:[1,0]
	ds_read2_b64 v[46:49], v76 offset0:64 offset1:68
	s_waitcnt lgkmcnt(0)
	v_mfma_f32_16x16x32_bf16 v[72:75], v[46:49], v[26:29], v[30:33]
	s_nop 2
	ds_read2_b64 v[30:33], v77 offset0:96 offset1:100
	v_pk_mul_f32 v[24:25], v[20:21], v[84:85] op_sel_hi:[1,0]
	v_cvt_pk_bf16_f32 v50, v132, v133
	v_mfma_f32_16x16x32_bf16 v[38:41], v[46:49], v[54:57], v[38:41]
	v_cvt_pk_bf16_f32 v51, v164, v165
	v_cvt_pk_bf16_f32 v52, v166, v167
	v_cvt_pk_bf16_f32 v53, v168, v169
	s_waitcnt lgkmcnt(0)
	v_mfma_f32_16x16x32_bf16 v[34:37], v[30:33], v[54:57], v[34:37]
	v_cvt_pk_bf16_f32 v18, v78, v79
	v_cvt_pk_bf16_f32 v20, v80, v81
	v_cvt_pk_bf16_f32 v21, v82, v83
	v_mfma_f32_16x16x32_bf16 v[54:57], v[30:33], v[26:29], v[22:25]
	s_mov_b64 s[0:1], 0x100
	v_add_u32_e32 v127, 64, v127
	v_lshl_add_u64 v[102:103], v[102:103], 0, s[0:1]
	ds_read2_b64 v[22:25], v125 offset0:8 offset1:12
	s_waitcnt lgkmcnt(0)
	v_mfma_f32_16x16x32_bf16 v[46:49], v[22:25], v[50:53], v[58:61]
	s_nop 2
	ds_read2_b64 v[58:61], v77 offset0:104 offset1:108
	v_add_u32_e32 v125, 0x4800, v125
	s_cmp_ge_i32 s9, s94
	v_mfma_f32_16x16x32_bf16 v[30:33], v[22:25], v[18:21], v[62:65]
	ds_read2_b64 v[22:25], v67 offset0:40 offset1:44
	v_mov_b32_e32 v109, v128
	s_waitcnt lgkmcnt(0)
	v_mfma_f32_16x16x32_bf16 v[42:45], v[22:25], v[50:53], v[42:45]
	v_mfma_f32_16x16x32_bf16 v[26:29], v[22:25], v[18:21], v[68:71]
	ds_read2_b64 v[22:25], v76 offset0:72 offset1:76
	s_waitcnt lgkmcnt(0)
	v_mfma_f32_16x16x32_bf16 v[38:41], v[22:25], v[50:53], v[38:41]
	v_mfma_f32_16x16x32_bf16 v[22:25], v[22:25], v[18:21], v[72:75]
	v_mfma_f32_16x16x32_bf16 v[34:37], v[58:61], v[50:53], v[34:37]
	v_mfma_f32_16x16x32_bf16 v[18:21], v[58:61], v[18:21], v[54:57]
	s_cbranch_scc0 .LBB0_276
	s_mov_b64 s[62:63], s[14:15]
	s_branch .LBB0_273
